# P3 attention first half-iteration: row max / scale-fma / exps moved from the barrier-to-barrier segment into the PV MFMA gaps (staging loads retargeted), on top of the VALU trims
# speedup vs baseline: 1.0100x; 1.0100x over previous
.LBB0_433:
	ds_read_b128 v[64:67], v166 offset:49152
	ds_read_b128 v[68:71], v166 offset:57344
	ds_read_b128 v[176:179], v167 offset:49152
	ds_read_b128 v[198:201], v167 offset:57344
	ds_read_b128 v[202:205], v168 offset:49152
	ds_read_b128 v[210:213], v168 offset:57344
	v_exp_f32_e32 v142, v142
	v_exp_f32_e32 v143, v143
	s_waitcnt lgkmcnt(5)
	v_mfma_f32_32x32x16_bf16 v[80:95], v[64:67], v[124:127], 0
	v_exp_f32_e32 v180, v140
	v_exp_f32_e32 v181, v141
	v_exp_f32_e32 v206, v138
	v_exp_f32_e32 v207, v135
	v_exp_f32_e32 v148, v148
	v_exp_f32_e32 v149, v149
	v_exp_f32_e32 v209, v146
	s_waitcnt lgkmcnt(4)
	v_mfma_f32_32x32x16_bf16 v[64:79], v[68:71], v[124:127], 0
	v_cvt_pk_bf16_f32 v135, v192, v193
	v_cvt_pk_bf16_f32 v138, v182, v183
	v_cvt_pk_bf16_f32 v140, v185, v187
	v_cvt_pk_bf16_f32 v141, v188, v189
	s_nop 0
	s_waitcnt lgkmcnt(3)
	v_mfma_f32_32x32x16_bf16 v[80:95], v[176:179], v[120:123], v[80:95]
	ds_read_b128 v[176:179], v169 offset:49152
	ds_read_b128 v[214:217], v169 offset:57344
	ds_read_b128 v[218:221], v170 offset:49152
	ds_read_b128 v[222:225], v170 offset:57344
	ds_read_b128 v[226:229], v171 offset:49152
	ds_read_b128 v[230:233], v171 offset:57344
	ds_read_b128 v[234:237], v172 offset:49152
	ds_read_b128 v[238:241], v172 offset:57344
	s_waitcnt lgkmcnt(10)
	v_mfma_f32_32x32x16_bf16 v[64:79], v[198:201], v[120:123], v[64:79]
	ds_read_b128 v[198:201], v173 offset:49152
	ds_read_b128 v[242:245], v173 offset:57344
	s_waitcnt lgkmcnt(11)
	v_mfma_f32_32x32x16_bf16 v[80:95], v[202:205], v[112:115], v[80:95]
	v_exp_f32_e32 v205, v134
	v_add_f32_e32 v134, v191, v190
	v_add_f32_e32 v134, v192, v134
	v_add_f32_e32 v134, v193, v134
	v_add_f32_e32 v134, v194, v134
	v_add_f32_e32 v134, v196, v134
	s_waitcnt lgkmcnt(10)
	v_mfma_f32_32x32x16_bf16 v[64:79], v[210:213], v[112:115], v[64:79]
	v_add_f32_e32 v134, v195, v134
	v_add_f32_e32 v134, v197, v134
	v_add_f32_e32 v134, v182, v134
	v_add_f32_e32 v134, v183, v134
	v_add_f32_e32 v134, v184, v134
	v_add_f32_e32 v134, v186, v134
	v_add_f32_e32 v134, v185, v134
	s_waitcnt lgkmcnt(9)
	v_mfma_f32_32x32x16_bf16 v[80:95], v[176:179], v[116:119], v[80:95]
	v_add_f32_e32 v134, v187, v134
	v_add_f32_e32 v134, v188, v134
	v_add_f32_e32 v134, v189, v134
	v_add_f32_e32 v134, v142, v134
	v_exp_f32_e32 v202, v139
	v_add_f32_e32 v134, v143, v134
	v_exp_f32_e32 v203, v136
	s_waitcnt lgkmcnt(8)
	v_mfma_f32_32x32x16_bf16 v[64:79], v[214:217], v[116:119], v[64:79]
	v_add_f32_e32 v134, v180, v134
	v_exp_f32_e32 v204, v137
	v_add_f32_e32 v134, v181, v134
	v_add_f32_e32 v134, v206, v134
	v_add_f32_e32 v134, v202, v134
	v_add_f32_e32 v134, v203, v134
	v_add_f32_e32 v134, v204, v134
	s_waitcnt lgkmcnt(7)
	v_mfma_f32_32x32x16_bf16 v[80:95], v[218:221], v[108:111], v[80:95]
	v_add_f32_e32 v134, v205, v134
	v_exp_f32_e32 v210, v147
	v_add_f32_e32 v134, v207, v134
	v_exp_f32_e32 v211, v144
	v_add_f32_e32 v134, v148, v134
	v_exp_f32_e32 v212, v145
	v_add_f32_e32 v134, v149, v134
	s_waitcnt lgkmcnt(6)
	v_mfma_f32_32x32x16_bf16 v[64:79], v[222:225], v[108:111], v[64:79]
	v_add_f32_e32 v134, v209, v134
	v_add_f32_e32 v134, v210, v134
	v_add_f32_e32 v134, v211, v134
	v_add_f32_e32 v176, v212, v134
	v_cvt_pk_bf16_f32 v134, v190, v191
	v_cvt_pk_bf16_f32 v136, v194, v196
	s_waitcnt lgkmcnt(5)
	v_mfma_f32_32x32x16_bf16 v[80:95], v[226:229], v[104:107], v[80:95]
	v_cvt_pk_bf16_f32 v137, v195, v197
	v_cvt_pk_bf16_f32 v139, v184, v186
	v_cvt_pk_bf16_f32 v142, v142, v143
	s_waitcnt lgkmcnt(4)
	v_mfma_f32_32x32x16_bf16 v[64:79], v[230:233], v[104:107], v[64:79]
	v_cvt_pk_bf16_f32 v143, v180, v181
	v_cvt_pk_bf16_f32 v144, v206, v202
	v_cvt_pk_bf16_f32 v145, v203, v204
	v_cvt_pk_bf16_f32 v146, v205, v207
	v_cvt_pk_bf16_f32 v147, v148, v149
	v_cvt_pk_bf16_f32 v148, v209, v210
	v_cvt_pk_bf16_f32 v149, v211, v212
	s_waitcnt lgkmcnt(3)
	v_mfma_f32_32x32x16_bf16 v[80:95], v[234:237], v[100:103], v[80:95]
	s_waitcnt lgkmcnt(2)
	v_mfma_f32_32x32x16_bf16 v[64:79], v[238:241], v[100:103], v[64:79]
	s_waitcnt lgkmcnt(1)
	v_mfma_f32_32x32x16_bf16 v[80:95], v[198:201], v[96:99], v[80:95]
	s_waitcnt lgkmcnt(0)
	v_mfma_f32_32x32x16_bf16 v[64:79], v[242:245], v[96:99], v[64:79]
	global_load_dwordx4 v[218:221], v132, s[28:29]
	global_load_dwordx4 v[222:225], v133, s[28:29]
	global_load_dwordx4 v[226:229], v132, s[30:31]
	global_load_dwordx4 v[230:233], v133, s[30:31]
	s_add_u32 s28, s28, 0x8000
	s_addc_u32 s29, s29, 0
	s_add_u32 s30, s30, 0x8000
	s_addc_u32 s31, s31, 0
	ds_read_b64_tr_b16 v[196:197], v161 offset:0
	ds_read_b64_tr_b16 v[198:199], v161 offset:0x800
	ds_read_b64_tr_b16 v[200:201], v161 offset:0x1000
	ds_read_b64_tr_b16 v[202:203], v161 offset:0x1800
	ds_read_b64_tr_b16 v[204:205], v161 offset:0x2000
	ds_read_b64_tr_b16 v[206:207], v161 offset:0x2800
	ds_read_b64_tr_b16 v[210:211], v161 offset:0x3000
	ds_read_b64_tr_b16 v[212:213], v161 offset:0x3800
	s_waitcnt lgkmcnt(0)
	s_nop 0
	v_mfma_f32_32x32x16_bf16 v[0:15], v[134:137], v[196:199], v[0:15]
	ds_read_b64_tr_b16 v[196:197], v161 offset:0x200
	ds_read_b64_tr_b16 v[198:199], v161 offset:0xa00
	v_max_f32_e32 v234, v80, v81
	v_max3_f32 v234, v234, v82, v83
	v_max3_f32 v234, v234, v84, v85
	v_max3_f32 v234, v234, v86, v87
	v_max3_f32 v234, v234, v88, v89
	v_mfma_f32_32x32x16_bf16 v[0:15], v[138:141], v[200:203], v[0:15]
	ds_read_b64_tr_b16 v[200:201], v161 offset:0x1200
	ds_read_b64_tr_b16 v[202:203], v161 offset:0x1a00
	v_max3_f32 v234, v234, v90, v91
	v_max3_f32 v234, v234, v92, v93
	v_max3_f32 v234, v234, v94, v95
	v_max3_f32 v234, v234, v64, v65
	v_max3_f32 v234, v234, v66, v67
	v_mfma_f32_32x32x16_bf16 v[0:15], v[142:145], v[204:207], v[0:15]
	ds_read_b64_tr_b16 v[204:205], v161 offset:0x2200
	ds_read_b64_tr_b16 v[206:207], v161 offset:0x2a00
	ds_read_b64_tr_b16 v[214:215], v161 offset:0x3200
	ds_read_b64_tr_b16 v[216:217], v161 offset:0x3a00
	v_max3_f32 v234, v234, v68, v69
	v_max3_f32 v234, v234, v70, v71
	v_max3_f32 v234, v234, v72, v73
	v_max3_f32 v234, v234, v74, v75
	v_max3_f32 v234, v234, v76, v77
	s_waitcnt lgkmcnt(0)
	v_mfma_f32_32x32x16_bf16 v[0:15], v[146:149], v[210:213], v[0:15]
	v_max3_f32 v234, v234, v78, v79
	v_mov_b32_e32 v235, v234
	v_mfma_f32_32x32x16_bf16 v[48:63], v[134:137], v[196:199], v[48:63]
	ds_read_b64_tr_b16 v[196:197], v161 offset:0x400
	ds_read_b64_tr_b16 v[198:199], v161 offset:0xc00
	v_permlane32_swap_b32_e32 v234, v235
	v_max_f32_e32 v234, v234, v235
	v_mfma_f32_32x32x16_bf16 v[48:63], v[138:141], v[200:203], v[48:63]
	ds_read_b64_tr_b16 v[200:201], v161 offset:0x1400
	ds_read_b64_tr_b16 v[202:203], v161 offset:0x1c00
	v_sub_f32_e32 v235, v234, v175
	v_max_f32_e32 v234, v175, v234
	v_sub_f32_e32 v236, v175, v234
	v_mul_f32_e32 v236, 0x3e0293ee, v236
	v_mfma_f32_32x32x16_bf16 v[48:63], v[142:145], v[204:207], v[48:63]
	ds_read_b64_tr_b16 v[204:205], v161 offset:0x2400
	ds_read_b64_tr_b16 v[206:207], v161 offset:0x2c00
	ds_read_b64_tr_b16 v[210:211], v161 offset:0x3400
	ds_read_b64_tr_b16 v[212:213], v161 offset:0x3c00
	v_exp_f32_e32 v236, v236
	v_cmp_ge_f32_e32 vcc, s15, v235
	s_cmp_eq_u64 vcc, exec
	s_cselect_b64 s[8:9], -1, 0
	s_waitcnt lgkmcnt(0)
	v_mfma_f32_32x32x16_bf16 v[48:63], v[146:149], v[214:217], v[48:63]
	v_cndmask_b32_e64 v179, v236, 1.0, s[8:9]
	v_cndmask_b32_e64 v234, v234, v175, s[8:9]
	v_mul_f32_e32 v238, 0xbe0293ee, v234
	v_pk_fma_f32 v[88:89], v[88:89], s[14:15], v[238:239] op_sel_hi:[1,0,0]
	v_pk_fma_f32 v[80:81], v[80:81], s[14:15], v[238:239] op_sel_hi:[1,0,0]
	v_mfma_f32_32x32x16_bf16 v[32:47], v[134:137], v[196:199], v[32:47]
	ds_read_b64_tr_b16 v[196:197], v161 offset:0x600
	ds_read_b64_tr_b16 v[198:199], v161 offset:0xe00
	v_pk_fma_f32 v[82:83], v[82:83], s[14:15], v[238:239] op_sel_hi:[1,0,0]
	v_pk_fma_f32 v[84:85], v[84:85], s[14:15], v[238:239] op_sel_hi:[1,0,0]
	v_pk_fma_f32 v[86:87], v[86:87], s[14:15], v[238:239] op_sel_hi:[1,0,0]
	v_pk_fma_f32 v[90:91], v[90:91], s[14:15], v[238:239] op_sel_hi:[1,0,0]
	v_mfma_f32_32x32x16_bf16 v[32:47], v[138:141], v[200:203], v[32:47]
	ds_read_b64_tr_b16 v[200:201], v161 offset:0x1600
	ds_read_b64_tr_b16 v[202:203], v161 offset:0x1e00
	v_pk_fma_f32 v[92:93], v[92:93], s[14:15], v[238:239] op_sel_hi:[1,0,0]
	v_pk_fma_f32 v[94:95], v[94:95], s[14:15], v[238:239] op_sel_hi:[1,0,0]
	v_pk_fma_f32 v[188:189], v[64:65], s[14:15], v[238:239] op_sel_hi:[1,0,0]
	v_pk_fma_f32 v[190:191], v[66:67], s[14:15], v[238:239] op_sel_hi:[1,0,0]
	v_mfma_f32_32x32x16_bf16 v[32:47], v[142:145], v[204:207], v[32:47]
	ds_read_b64_tr_b16 v[204:205], v161 offset:0x2600
	ds_read_b64_tr_b16 v[206:207], v161 offset:0x2e00
	ds_read_b64_tr_b16 v[214:215], v161 offset:0x3600
	ds_read_b64_tr_b16 v[216:217], v161 offset:0x3e00
	v_pk_fma_f32 v[182:183], v[70:71], s[14:15], v[238:239] op_sel_hi:[1,0,0]
	v_pk_fma_f32 v[184:185], v[72:73], s[14:15], v[238:239] op_sel_hi:[1,0,0]
	v_pk_fma_f32 v[186:187], v[74:75], s[14:15], v[238:239] op_sel_hi:[1,0,0]
	s_waitcnt lgkmcnt(0)
	v_mfma_f32_32x32x16_bf16 v[32:47], v[146:149], v[210:213], v[32:47]
	v_fmamk_f32 v192, v68, 0x3e0293ee, v238
	v_fmamk_f32 v181, v69, 0x3e0293ee, v238
	v_fmamk_f32 v180, v76, 0x3e0293ee, v238
	v_mfma_f32_32x32x16_bf16 v[16:31], v[134:137], v[196:199], v[16:31]
	v_fmamk_f32 v193, v77, 0x3e0293ee, v238
	v_fmamk_f32 v194, v78, 0x3e0293ee, v238
	v_fmamk_f32 v177, v79, 0x3e0293ee, v238
	v_mov_b32_e32 v134, v234
	v_exp_f32_e32 v135, v88
	v_exp_f32_e32 v136, v89
	v_exp_f32_e32 v137, v90
	v_mfma_f32_32x32x16_bf16 v[16:31], v[138:141], v[200:203], v[16:31]
	v_exp_f32_e32 v139, v91
	v_exp_f32_e32 v138, v92
	v_exp_f32_e32 v140, v93
	v_exp_f32_e32 v141, v94
	v_mfma_f32_32x32x16_bf16 v[16:31], v[142:145], v[204:207], v[16:31]
	v_exp_f32_e32 v142, v95
	v_exp_f32_e32 v143, v80
	v_exp_f32_e32 v144, v81
	v_exp_f32_e32 v145, v82
	v_mfma_f32_32x32x16_bf16 v[16:31], v[146:149], v[214:217], v[16:31]
	v_exp_f32_e32 v146, v83
	v_exp_f32_e32 v147, v84
	v_exp_f32_e32 v149, v85
	v_exp_f32_e32 v148, v86
	v_exp_f32_e32 v175, v87
	v_cmp_gt_f32_e32 vcc, 1.0, v179
	s_barrier
	s_waitcnt vmcnt(0)
	ds_write_b128 v164, v[218:221]
	ds_write_b128 v165, v[222:225]
	ds_write_b128 v162, v[226:229] offset:32768
	ds_write_b128 v163, v[230:233] offset:32768
	s_cbranch_vccz .LBB0_437
	s_and_saveexec_b64 s[2:3], s[6:7]
	ds_write_b32 v158, v179 offset:128
	s_or_b64 exec, exec, s[2:3]
	s_waitcnt lgkmcnt(0)
	v_add_u32_e32 v234, v131, v128
	ds_read_b128 v[218:221], v234 offset:224
	ds_read_b128 v[222:225], v234 offset:192
	ds_read_b128 v[226:229], v234 offset:160
	ds_read_b128 v[230:233], v234 offset:128
	s_waitcnt lgkmcnt(3)
	v_pk_mul_f32 v[12:13], v[12:13], v[218:219]
	s_waitcnt lgkmcnt(2)
	v_pk_mul_f32 v[8:9], v[8:9], v[222:223]
	s_waitcnt lgkmcnt(1)
	v_pk_mul_f32 v[4:5], v[4:5], v[226:227]
	v_pk_mul_f32 v[14:15], v[14:15], v[220:221]
	v_pk_mul_f32 v[10:11], v[10:11], v[224:225]
	v_pk_mul_f32 v[6:7], v[6:7], v[228:229]
	s_waitcnt lgkmcnt(0)
	v_pk_mul_f32 v[2:3], v[2:3], v[232:233]
	v_pk_mul_f32 v[0:1], v[0:1], v[230:231]
	v_pk_mul_f32 v[60:61], v[60:61], v[218:219]
	v_pk_mul_f32 v[56:57], v[56:57], v[222:223]
	v_pk_mul_f32 v[52:53], v[52:53], v[226:227]
	v_pk_mul_f32 v[62:63], v[62:63], v[220:221]
	v_pk_mul_f32 v[58:59], v[58:59], v[224:225]
	v_pk_mul_f32 v[54:55], v[54:55], v[228:229]
	v_pk_mul_f32 v[50:51], v[50:51], v[232:233]
	v_pk_mul_f32 v[48:49], v[48:49], v[230:231]
	v_pk_mul_f32 v[44:45], v[44:45], v[218:219]
	v_pk_mul_f32 v[40:41], v[40:41], v[222:223]
	v_pk_mul_f32 v[36:37], v[36:37], v[226:227]
	v_pk_mul_f32 v[46:47], v[46:47], v[220:221]
	v_pk_mul_f32 v[42:43], v[42:43], v[224:225]
	v_pk_mul_f32 v[38:39], v[38:39], v[228:229]
	v_pk_mul_f32 v[34:35], v[34:35], v[232:233]
	v_pk_mul_f32 v[32:33], v[32:33], v[230:231]
	v_pk_mul_f32 v[28:29], v[28:29], v[218:219]
	v_pk_mul_f32 v[24:25], v[24:25], v[222:223]
	v_pk_mul_f32 v[20:21], v[20:21], v[226:227]
	v_pk_mul_f32 v[30:31], v[30:31], v[220:221]
	v_pk_mul_f32 v[26:27], v[26:27], v[224:225]
	v_pk_mul_f32 v[22:23], v[22:23], v[228:229]
	v_pk_mul_f32 v[18:19], v[18:19], v[232:233]
	v_pk_mul_f32 v[16:17], v[16:17], v[230:231]
.LBB0_437:
	s_waitcnt lgkmcnt(0)
	s_barrier
	ds_read_b128 v[64:67], v166 offset:32768
	ds_read_b128 v[68:71], v166 offset:40960
	ds_read_b128 v[196:199], v167 offset:32768
	ds_read_b128 v[200:203], v167 offset:40960
	ds_read_b128 v[204:207], v168 offset:32768
	ds_read_b128 v[210:213], v168 offset:40960
	v_exp_f32_e32 v188, v188
	v_exp_f32_e32 v189, v189
	s_waitcnt lgkmcnt(5)
	v_mfma_f32_32x32x16_bf16 v[80:95], v[64:67], v[124:127], 0
	v_exp_f32_e32 v190, v190
	v_exp_f32_e32 v191, v191
	v_exp_f32_e32 v192, v192
	v_exp_f32_e32 v195, v181
	v_exp_f32_e32 v182, v182
	v_exp_f32_e32 v183, v183
	v_exp_f32_e32 v184, v184
	s_waitcnt lgkmcnt(4)
	v_mfma_f32_32x32x16_bf16 v[64:79], v[68:71], v[124:127], 0
	v_exp_f32_e32 v185, v185
	v_exp_f32_e32 v186, v186
	v_exp_f32_e32 v187, v187
	v_exp_f32_e32 v193, v193
	v_exp_f32_e32 v194, v194
	v_exp_f32_e32 v177, v177
	s_waitcnt lgkmcnt(3)
	v_mfma_f32_32x32x16_bf16 v[80:95], v[196:199], v[120:123], v[80:95]
	ds_read_b128 v[196:199], v169 offset:32768
	ds_read_b128 v[214:217], v169 offset:40960
	ds_read_b128 v[218:221], v170 offset:32768
	ds_read_b128 v[222:225], v170 offset:40960
	ds_read_b128 v[226:229], v171 offset:32768
	ds_read_b128 v[230:233], v171 offset:40960
	ds_read_b128 v[234:237], v172 offset:32768
	ds_read_b128 v[238:241], v172 offset:40960
	s_waitcnt lgkmcnt(10)
	v_mfma_f32_32x32x16_bf16 v[64:79], v[200:203], v[120:123], v[64:79]
	ds_read_b128 v[200:203], v173 offset:32768
	ds_read_b128 v[242:245], v173 offset:40960
	s_waitcnt lgkmcnt(11)
	v_mfma_f32_32x32x16_bf16 v[80:95], v[204:207], v[112:115], v[80:95]
	v_exp_f32_e32 v204, v180
	v_add_f32_e32 v180, v144, v143
	v_add_f32_e32 v180, v145, v180
	v_add_f32_e32 v180, v146, v180
	v_add_f32_e32 v180, v147, v180
	v_add_f32_e32 v180, v149, v180
	s_waitcnt lgkmcnt(10)
	v_mfma_f32_32x32x16_bf16 v[64:79], v[210:213], v[112:115], v[64:79]
	v_add_f32_e32 v180, v148, v180
	v_add_f32_e32 v180, v175, v180
	v_add_f32_e32 v180, v135, v180
	v_add_f32_e32 v180, v136, v180
	v_add_f32_e32 v180, v137, v180
	v_add_f32_e32 v180, v139, v180
	v_add_f32_e32 v180, v138, v180
	s_waitcnt lgkmcnt(9)
	v_mfma_f32_32x32x16_bf16 v[80:95], v[196:199], v[116:119], v[80:95]
	v_add_f32_e32 v180, v140, v180
	v_add_f32_e32 v180, v141, v180
	v_add_f32_e32 v180, v142, v180
	v_add_f32_e32 v180, v188, v180
	v_add_f32_e32 v180, v189, v180
	v_add_f32_e32 v180, v190, v180
	v_add_f32_e32 v180, v191, v180
	s_waitcnt lgkmcnt(8)
	v_mfma_f32_32x32x16_bf16 v[64:79], v[214:217], v[116:119], v[64:79]
	v_add_f32_e32 v180, v192, v180
	v_add_f32_e32 v180, v195, v180
	v_add_f32_e32 v180, v182, v180
	v_add_f32_e32 v180, v183, v180
	v_add_f32_e32 v180, v184, v180
	v_add_f32_e32 v180, v185, v180
	v_add_f32_e32 v180, v186, v180
	s_waitcnt lgkmcnt(7)
	v_mfma_f32_32x32x16_bf16 v[80:95], v[218:221], v[108:111], v[80:95]
	v_add_f32_e32 v180, v187, v180
	v_add_f32_e32 v180, v204, v180
	v_add_f32_e32 v180, v193, v180
	v_add_f32_e32 v180, v194, v180
	v_add_f32_e32 v180, v177, v180
	s_waitcnt lgkmcnt(6)
	v_mfma_f32_32x32x16_bf16 v[64:79], v[222:225], v[108:111], v[64:79]
	v_cvt_pk_bf16_f32 v144, v143, v144
	v_cvt_pk_bf16_f32 v145, v145, v146
	v_cvt_pk_bf16_f32 v146, v147, v149
	v_cvt_pk_bf16_f32 v147, v148, v175
	v_cvt_pk_bf16_f32 v136, v135, v136
	v_cvt_pk_bf16_f32 v137, v137, v139
	v_cvt_pk_bf16_f32 v138, v138, v140
	s_waitcnt lgkmcnt(5)
	v_mfma_f32_32x32x16_bf16 v[80:95], v[226:229], v[104:107], v[80:95]
	v_cvt_pk_bf16_f32 v139, v141, v142
	v_cvt_pk_bf16_f32 v140, v188, v189
	v_cvt_pk_bf16_f32 v141, v190, v191
	v_cvt_pk_bf16_f32 v142, v192, v195
	v_cvt_pk_bf16_f32 v143, v182, v183
	v_cvt_pk_bf16_f32 v182, v184, v185
	v_cvt_pk_bf16_f32 v183, v186, v187
	s_waitcnt lgkmcnt(4)
	v_mfma_f32_32x32x16_bf16 v[64:79], v[230:233], v[104:107], v[64:79]
	v_cvt_pk_bf16_f32 v184, v204, v193
	v_cvt_pk_bf16_f32 v185, v194, v177
	s_waitcnt lgkmcnt(3)
	v_mfma_f32_32x32x16_bf16 v[80:95], v[234:237], v[100:103], v[80:95]
	s_waitcnt lgkmcnt(2)
	v_mfma_f32_32x32x16_bf16 v[64:79], v[238:241], v[100:103], v[64:79]
	s_waitcnt lgkmcnt(1)
	v_mfma_f32_32x32x16_bf16 v[80:95], v[200:203], v[96:99], v[80:95]
	s_waitcnt lgkmcnt(0)
	v_mfma_f32_32x32x16_bf16 v[64:79], v[242:245], v[96:99], v[64:79]
	global_load_dwordx4 v[186:189], v132, s[28:29]
	global_load_dwordx4 v[190:193], v132, s[30:31]
	global_load_dwordx4 v[194:197], v133, s[28:29]
	global_load_dwordx4 v[198:201], v133, s[30:31]
	s_add_u32 s28, s28, 0x8000
	s_addc_u32 s29, s29, 0
	s_add_u32 s30, s30, 0x8000
	s_addc_u32 s31, s31, 0
	ds_read_b64_tr_b16 v[202:203], v160 offset:0
	ds_read_b64_tr_b16 v[204:205], v160 offset:0x800
	ds_read_b64_tr_b16 v[210:211], v160 offset:0x1000
	ds_read_b64_tr_b16 v[212:213], v160 offset:0x1800
	ds_read_b64_tr_b16 v[214:215], v160 offset:0x2000
	ds_read_b64_tr_b16 v[216:217], v160 offset:0x2800
	ds_read_b64_tr_b16 v[218:219], v160 offset:0x3000
	ds_read_b64_tr_b16 v[220:221], v160 offset:0x3800
	s_waitcnt lgkmcnt(0)
	s_nop 0
	v_mfma_f32_32x32x16_bf16 v[0:15], v[144:147], v[202:205], v[0:15]
	ds_read_b64_tr_b16 v[202:203], v160 offset:0x200
	ds_read_b64_tr_b16 v[204:205], v160 offset:0xa00
	v_mfma_f32_32x32x16_bf16 v[0:15], v[136:139], v[210:213], v[0:15]
	ds_read_b64_tr_b16 v[210:211], v160 offset:0x1200
	ds_read_b64_tr_b16 v[212:213], v160 offset:0x1a00
	v_mfma_f32_32x32x16_bf16 v[0:15], v[140:143], v[214:217], v[0:15]
	ds_read_b64_tr_b16 v[214:215], v160 offset:0x2200
	ds_read_b64_tr_b16 v[216:217], v160 offset:0x2a00
	ds_read_b64_tr_b16 v[222:223], v160 offset:0x3200
	ds_read_b64_tr_b16 v[224:225], v160 offset:0x3a00
	s_waitcnt lgkmcnt(0)
	v_mfma_f32_32x32x16_bf16 v[0:15], v[182:185], v[218:221], v[0:15]
	v_mfma_f32_32x32x16_bf16 v[48:63], v[144:147], v[202:205], v[48:63]
	ds_read_b64_tr_b16 v[202:203], v160 offset:0x400
	ds_read_b64_tr_b16 v[204:205], v160 offset:0xc00
	v_mfma_f32_32x32x16_bf16 v[48:63], v[136:139], v[210:213], v[48:63]
	ds_read_b64_tr_b16 v[210:211], v160 offset:0x1400
	ds_read_b64_tr_b16 v[212:213], v160 offset:0x1c00
	v_mfma_f32_32x32x16_bf16 v[48:63], v[140:143], v[214:217], v[48:63]
	ds_read_b64_tr_b16 v[214:215], v160 offset:0x2400
	ds_read_b64_tr_b16 v[216:217], v160 offset:0x2c00
	ds_read_b64_tr_b16 v[218:219], v160 offset:0x3400
	ds_read_b64_tr_b16 v[220:221], v160 offset:0x3c00
	s_waitcnt lgkmcnt(0)
	v_mfma_f32_32x32x16_bf16 v[48:63], v[182:185], v[222:225], v[48:63]
	v_mfma_f32_32x32x16_bf16 v[32:47], v[144:147], v[202:205], v[32:47]
	ds_read_b64_tr_b16 v[202:203], v160 offset:0x600
	ds_read_b64_tr_b16 v[204:205], v160 offset:0xe00
	v_mfma_f32_32x32x16_bf16 v[32:47], v[136:139], v[210:213], v[32:47]
	ds_read_b64_tr_b16 v[210:211], v160 offset:0x1600
	ds_read_b64_tr_b16 v[212:213], v160 offset:0x1e00
	v_mfma_f32_32x32x16_bf16 v[32:47], v[140:143], v[214:217], v[32:47]
	ds_read_b64_tr_b16 v[214:215], v160 offset:0x2600
	ds_read_b64_tr_b16 v[216:217], v160 offset:0x2e00
	ds_read_b64_tr_b16 v[222:223], v160 offset:0x3600
	ds_read_b64_tr_b16 v[224:225], v160 offset:0x3e00
	s_waitcnt lgkmcnt(0)
	v_mfma_f32_32x32x16_bf16 v[32:47], v[182:185], v[218:221], v[32:47]
	v_mfma_f32_32x32x16_bf16 v[16:31], v[144:147], v[202:205], v[16:31]
	v_max_f32_e32 v135, v80, v81
	v_max3_f32 v135, v135, v82, v83
	v_max3_f32 v135, v135, v84, v85
	v_max3_f32 v135, v135, v86, v87
	v_max3_f32 v135, v135, v88, v89
	v_max3_f32 v135, v135, v90, v91
	v_mfma_f32_32x32x16_bf16 v[16:31], v[136:139], v[210:213], v[16:31]
	v_max3_f32 v135, v135, v92, v93
	v_max3_f32 v135, v135, v94, v95
	v_max3_f32 v135, v135, v64, v65
	v_max3_f32 v135, v135, v66, v67
	v_max3_f32 v135, v135, v68, v69
	v_max3_f32 v135, v135, v70, v71
	v_max3_f32 v135, v135, v72, v73
	v_max3_f32 v135, v135, v74, v75
	v_mfma_f32_32x32x16_bf16 v[16:31], v[140:143], v[214:217], v[16:31]
	v_max3_f32 v135, v135, v76, v77
	v_max3_f32 v135, v135, v78, v79
	v_mov_b32_e32 v136, v135
	s_nop 1
	v_permlane32_swap_b32_e32 v135, v136
	v_max_f32_e32 v135, v135, v136
	v_sub_f32_e32 v136, v135, v134
	v_max_f32_e32 v135, v134, v135
	v_mfma_f32_32x32x16_bf16 v[16:31], v[182:185], v[222:225], v[16:31]
	v_sub_f32_e32 v137, v134, v135
	v_mul_f32_e32 v137, 0x3e0293ee, v137
	v_exp_f32_e32 v137, v137
	v_cmp_ge_f32_e32 vcc, s15, v136
	s_cmp_eq_u64 vcc, exec
	s_cselect_b64 s[8:9], -1, 0
	s_barrier
	s_waitcnt vmcnt(0)
	v_cndmask_b32_e64 v177, v137, 1.0, s[8:9]
	v_cmp_gt_f32_e32 vcc, 1.0, v177
	s_waitcnt vmcnt(3)
	ds_write_b128 v164, v[186:189] offset:16384
	s_waitcnt vmcnt(1)
	ds_write_b128 v165, v[194:197] offset:16384
	ds_write_b128 v162, v[190:193] offset:49152
	s_waitcnt vmcnt(0)
	ds_write_b128 v163, v[198:201] offset:49152
	s_cbranch_vccz .LBB0_441
	s_and_saveexec_b64 s[2:3], s[6:7]
	ds_write_b32 v158, v177 offset:128
	s_or_b64 exec, exec, s[2:3]
	s_waitcnt lgkmcnt(0)
	v_add_u32_e32 v148, v131, v128
	ds_read_b128 v[136:139], v148 offset:224
	ds_read_b128 v[140:143], v148 offset:192
	ds_read_b128 v[144:147], v148 offset:160
	ds_read_b128 v[182:185], v148 offset:128
	s_waitcnt lgkmcnt(3)
	v_pk_mul_f32 v[12:13], v[12:13], v[136:137]
	s_waitcnt lgkmcnt(2)
	v_pk_mul_f32 v[8:9], v[8:9], v[140:141]
	s_waitcnt lgkmcnt(1)
	v_pk_mul_f32 v[4:5], v[4:5], v[144:145]
	v_pk_mul_f32 v[14:15], v[14:15], v[138:139]
	v_pk_mul_f32 v[10:11], v[10:11], v[142:143]
	v_pk_mul_f32 v[6:7], v[6:7], v[146:147]
	s_waitcnt lgkmcnt(0)
	v_pk_mul_f32 v[2:3], v[2:3], v[184:185]
	v_pk_mul_f32 v[0:1], v[0:1], v[182:183]
	v_pk_mul_f32 v[60:61], v[60:61], v[136:137]
	v_pk_mul_f32 v[56:57], v[56:57], v[140:141]
	v_pk_mul_f32 v[52:53], v[52:53], v[144:145]
	v_pk_mul_f32 v[62:63], v[62:63], v[138:139]
	v_pk_mul_f32 v[58:59], v[58:59], v[142:143]
	v_pk_mul_f32 v[54:55], v[54:55], v[146:147]
	v_pk_mul_f32 v[50:51], v[50:51], v[184:185]
	v_pk_mul_f32 v[48:49], v[48:49], v[182:183]
	v_pk_mul_f32 v[44:45], v[44:45], v[136:137]
	v_pk_mul_f32 v[40:41], v[40:41], v[140:141]
	v_pk_mul_f32 v[36:37], v[36:37], v[144:145]
	v_pk_mul_f32 v[46:47], v[46:47], v[138:139]
	v_pk_mul_f32 v[42:43], v[42:43], v[142:143]
	v_pk_mul_f32 v[38:39], v[38:39], v[146:147]
	v_pk_mul_f32 v[34:35], v[34:35], v[184:185]
	v_pk_mul_f32 v[32:33], v[32:33], v[182:183]
	v_pk_mul_f32 v[28:29], v[28:29], v[136:137]
	v_pk_mul_f32 v[24:25], v[24:25], v[140:141]
	v_pk_mul_f32 v[20:21], v[20:21], v[144:145]
	v_pk_mul_f32 v[30:31], v[30:31], v[138:139]
	v_pk_mul_f32 v[26:27], v[26:27], v[142:143]
	v_pk_mul_f32 v[22:23], v[22:23], v[146:147]
	v_pk_mul_f32 v[18:19], v[18:19], v[184:185]
	v_pk_mul_f32 v[16:17], v[16:17], v[182:183]
